# MLA tile start: first K fragment pair read, then the global K/V loads, then the other K fragment reads
# speedup vs baseline: 1.0027x; 1.0027x over previous
; __device__ __forceinline__ unsigned pk4_fp8(float a, float b, float c, float d) { int p = __builtin_amdgcn_cvt_pk_fp8_f32(a, b, 0, false); p = __builtin_amdgcn_cvt_pk_fp8_f32(c, d, p, true); return (unsigned)p; }
; template <int MODE>
; __device__ __forceinline__ void qkt(f32x16& p0, f32x16& p1, const char* Ks, const char* Krs, const char* Qrs, const bf16x8* qr, const i32x8* q8, int r32, int hi) {
;     ...
;     for (int kb = 0; kb < 3; ++kb) {
; #pragma unroll
;       for (int hf = 0; hf < 2; ++hf) { const char* a_ = Ks + (hf * 32 + r32) * 208 + kb * 64 + hi * 32;
;         const u32x4 lo = *reinterpret_cast<const u32x4*>(a_), h4 = *reinterpret_cast<const u32x4*>(a_ + 16);
;         const i32x8 a = {(int)lo.x, (int)lo.y, (int)lo.z, (int)lo.w, (int)h4.x, (int)h4.y, (int)h4.z, (int)h4.w};
;         if (hf) p1 = __builtin_amdgcn_mfma_scale_f32_32x32x64_f8f6f4(a, q8[kb], p1, 0, 0, 0, 0x7F7F7F7F, 0, 0x7F7F7F7F);
;         else p0 = __builtin_amdgcn_mfma_scale_f32_32x32x64_f8f6f4(a, q8[kb], p0, 0, 0, 0, 0x7F7F7F7F, 0, 0x7F7F7F7F); } }
; __device__ __forceinline__ void finishSM8(f32x16& p0, f32x16& p1, float alpha, float& l_reg, bf16x8& pa0, bf16x8& pa1) {
; #pragma unroll
;   for (int r = 0; r < 16; ++r) p1[r] = __builtin_amdgcn_exp2f(p1[r]);
;   float ps = 0;
; #pragma unroll
;   for (int r = 0; r < 16; ++r) ps += p0[r];
; #pragma unroll
;   for (int r = 0; r < 16; ++r) ps += p1[r];
;   { auto rr = __builtin_amdgcn_permlane32_swap(__float_as_uint(ps), __float_as_uint(ps), false, false); ps = __uint_as_float(rr[0]) + __uint_as_float(rr[1]); }
;   l_reg = l_reg * alpha + ps;
;   const u32x4 w0 = {pk4_fp8(p0[0], p0[1], p0[2], p0[3]), pk4_fp8(p0[4], p0[5], p0[6], p0[7]), pk4_fp8(p0[8], p0[9], p0[10], p0[11]), pk4_fp8(p0[12], p0[13], p0[14], p0[15])};
;   const u32x4 w1 = {pk4_fp8(p1[0], p1[1], p1[2], p1[3]), pk4_fp8(p1[4], p1[5], p1[6], p1[7]), pk4_fp8(p1[8], p1[9], p1[10], p1[11]), pk4_fp8(p1[12], p1[13], p1[14], p1[15])};
;   pa0 = __builtin_bit_cast(bf16x8, w0); pa1 = __builtin_bit_cast(bf16x8, w1);
.LBB0_655:
	ds_read_b128 v[82:85], v231 offset:49152
	ds_read_b128 v[86:89], v231 offset:49168
	global_load_dwordx4 v[182:185], v[208:209], off
	global_load_dwordx4 v[186:189], v[206:207], off
	s_and_saveexec_b64 s[20:21], s[12:13]
	global_load_dwordx4 v[178:181], v[204:205], off
	s_or_b64 exec, exec, s[20:21]
	v_lshl_add_u64 v[206:207], v[206:207], 0, v[212:213]
	v_lshl_add_u64 v[204:205], v[204:205], 0, v[210:211]
	ds_read_b128 v[122:125], v231 offset:49216
	ds_read_b128 v[126:129], v231 offset:49232
	ds_read_b128 v[162:165], v231 offset:49280
	ds_read_b128 v[166:169], v231 offset:49296
	ds_read_b128 v[146:149], v231 offset:55808
	ds_read_b128 v[150:153], v231 offset:55824
	ds_read_b128 v[154:157], v231 offset:55872
	ds_read_b128 v[158:161], v231 offset:55888
	ds_read_b128 v[170:173], v231 offset:55936
	ds_read_b128 v[174:177], v231 offset:55952
	s_waitcnt lgkmcnt(10)
	v_mfma_scale_f32_32x32x64_f8f6f4 v[82:97], v[82:89], v[114:121], 0, v216, v216 op_sel_hi:[0,0,0]
	v_exp_f32_e32 v240, v98
	v_exp_f32_e32 v242, v99
	v_exp_f32_e32 v239, v100
	v_exp_f32_e32 v241, v101
	v_exp_f32_e32 v245, v102
	v_exp_f32_e32 v246, v103
	v_add_f32_e32 v0, 0, v66
	v_add_f32_e32 v0, v67, v0
	s_waitcnt lgkmcnt(8)
	v_mfma_scale_f32_32x32x64_f8f6f4 v[82:97], v[122:129], v[130:137], v[82:97], v216, v216 op_sel_hi:[0,0,0]
	v_exp_f32_e32 v243, v104
	v_exp_f32_e32 v244, v105
	v_exp_f32_e32 v247, v106
	v_exp_f32_e32 v250, v107
	v_exp_f32_e32 v248, v108
	v_exp_f32_e32 v249, v109
	v_add_f32_e32 v0, v68, v0
	v_add_f32_e32 v236, v242, v240
	v_add_f32_e32 v0, v69, v0
	v_add_f32_e32 v236, v239, v236
	v_add_f32_e32 v236, v241, v236
	s_waitcnt lgkmcnt(6)
	v_mfma_scale_f32_32x32x64_f8f6f4 v[82:97], v[162:169], v[138:145], v[82:97], v216, v216 op_sel_hi:[0,0,0]
	v_exp_f32_e32 v191, v110
	v_exp_f32_e32 v217, v111
	v_exp_f32_e32 v251, v112
	v_exp_f32_e32 v252, v113
	v_add_f32_e32 v0, v70, v0
	v_add_f32_e32 v236, v245, v236
	v_add_f32_e32 v0, v71, v0
	v_add_f32_e32 v236, v246, v236
	v_add_f32_e32 v0, v72, v0
	v_add_f32_e32 v236, v243, v236
	v_add_f32_e32 v0, v73, v0
	v_add_f32_e32 v236, v244, v236
	s_waitcnt lgkmcnt(4)
	v_mfma_scale_f32_32x32x64_f8f6f4 v[98:113], v[146:153], v[114:121], 0, v216, v216 op_sel_hi:[0,0,0]
	v_add_f32_e32 v0, v74, v0
	v_add_f32_e32 v236, v247, v236
	v_add_f32_e32 v0, v75, v0
	v_add_f32_e32 v236, v250, v236
	v_add_f32_e32 v0, v76, v0
	v_add_f32_e32 v236, v248, v236
	v_add_f32_e32 v0, v77, v0
	v_add_f32_e32 v236, v249, v236
	v_add_f32_e32 v0, v78, v0
	v_add_f32_e32 v236, v191, v236
	s_waitcnt lgkmcnt(2)
	v_mfma_scale_f32_32x32x64_f8f6f4 v[98:113], v[154:161], v[130:137], v[98:113], v216, v216 op_sel_hi:[0,0,0]
	v_add_f32_e32 v0, v79, v0
	v_add_f32_e32 v236, v217, v236
	v_add_f32_e32 v0, v80, v0
	v_add_f32_e32 v236, v251, v236
	v_add_f32_e32 v0, v81, v0
	v_add_f32_e32 v236, v252, v236
	v_add_f32_e32 v235, v236, v0
	v_mov_b32_e32 v236, v235
	s_waitcnt lgkmcnt(0)
	v_mfma_scale_f32_32x32x64_f8f6f4 v[98:113], v[170:177], v[138:145], v[98:113], v216, v216 op_sel_hi:[0,0,0]
	s_nop 0
	v_permlane32_swap_b32_e32 v235, v236
	ds_read_b128 v[154:157], v230
	ds_read_b128 v[158:161], v230 offset:16
	ds_read_b128 v[146:149], v230 offset:2560
	ds_read_b128 v[150:153], v230 offset:2576
	ds_read_b128 v[122:125], v230 offset:5120
	ds_read_b128 v[126:129], v230 offset:5136
	ds_read_b128 v[166:169], v230 offset:7696
	v_cvt_pk_fp8_f32 v170, v66, v67
	v_cvt_pk_fp8_f32 v171, v70, v71
	v_cvt_pk_fp8_f32 v172, v74, v75
	v_cvt_pk_fp8_f32 v173, v78, v79
	v_cvt_pk_fp8_f32 v174, v240, v242
	v_cvt_pk_fp8_f32 v175, v245, v246
	v_cvt_pk_fp8_f32 v176, v247, v250
	v_cvt_pk_fp8_f32 v177, v191, v217
	v_cvt_pk_fp8_f32 v170, v68, v69 op_sel:[0,0,1]
	v_cvt_pk_fp8_f32 v171, v72, v73 op_sel:[0,0,1]
	v_cvt_pk_fp8_f32 v172, v76, v77 op_sel:[0,0,1]
	v_cvt_pk_fp8_f32 v173, v80, v81 op_sel:[0,0,1]
	v_cvt_pk_fp8_f32 v174, v239, v241 op_sel:[0,0,1]
	v_cvt_pk_fp8_f32 v175, v243, v244 op_sel:[0,0,1]
	v_cvt_pk_fp8_f32 v176, v248, v249 op_sel:[0,0,1]
	v_cvt_pk_fp8_f32 v177, v251, v252 op_sel:[0,0,1]
	v_max_f32_e32 v0, v83, v83
	v_max_f32_e32 v163, v98, v98
	v_max_f32_e32 v162, v82, v82
	v_max3_f32 v163, v163, v99, v100
	v_max_f32_e32 v0, v162, v0
	v_max3_f32 v163, v163, v101, v102
	v_max3_f32 v0, v0, v84, v85
	v_max3_f32 v163, v163, v103, v104
	v_max3_f32 v0, v0, v86, v87
	v_max3_f32 v163, v163, v105, v106
	v_max3_f32 v0, v0, v88, v89
	v_max3_f32 v163, v163, v107, v108
	v_max3_f32 v0, v0, v90, v91
	v_max3_f32 v163, v163, v109, v110
	v_max3_f32 v0, v0, v92, v93
	v_max3_f32 v163, v163, v111, v112
	v_max3_f32 v0, v0, v94, v95
	v_max_f32_e32 v163, v163, v113
	v_max3_f32 v0, v0, v96, v97
	v_max_f32_e32 v0, v0, v163
	v_mov_b32_e32 v162, v0
	s_nop 1
	v_permlane32_swap_b32_e32 v0, v162
	v_max_f32_e32 v162, v162, v162
	v_max_f32_e32 v0, v0, v0
	v_max_f32_e32 v0, v0, v162
	v_sub_f32_e32 v162, v0, v237
	v_mul_f32_e32 v162, 0x3dd53b94, v162
	v_cmp_ge_f32_e32 vcc, s57, v162
	s_cmp_eq_u64 vcc, exec
	v_max_f32_e32 v162, v237, v237
	s_cselect_b64 vcc, -1, 0
	v_max_f32_e32 v0, v162, v0
	v_cndmask_b32_e32 v238, v0, v237, vcc
	v_sub_f32_e32 v0, v237, v238
	v_mul_f32_e32 v0, 0x3dd53b94, v0
	v_exp_f32_e32 v0, v0
	ds_read_b128 v[162:165], v230 offset:7680
	s_waitcnt lgkmcnt(0)
; #define SBAR() __builtin_amdgcn_sched_barrier(0)
; #define PVC(voff) do { if constexpr (MODE == 0) pv8(o, V_lds + (voff), pa0, pa1, r32, hi); else pv_d0(o, vb0 + (voff), pa0, pa1, pa2, pa3); } while (0)
; #define FSM(P0, P1, AL) do { if constexpr (MODE == 0) finishSM8(P0, P1, AL, l_reg, pa0, pa1); else finishSM(P0, P1, AL, l_reg, pa0, pa1, pa2, pa3); } while (0)
; #define SWAIT() do { if constexpr (SD == 1) asm volatile("s_waitcnt vmcnt(0)" ::: "memory"); else if constexpr (MODE == 0) asm volatile("s_waitcnt vmcnt(5)" ::: "memory"); else asm volatile("s_waitcnt vmcnt(4)" ::: "memory"); } while (0)
; #define SG_QKT() do { if (SGQ) { __builtin_amdgcn_sched_group_barrier(0x100, SGQ_PRE, 0); if constexpr (MODE == 0) { _Pragma("unroll") for (int _g = 0; _g < 6; ++_g) SG_ONE(2, 12, 3); } else { _Pragma("unroll") for (int _g = 0; _g < 16; ++_g) SG_ONE(1, 5, 1); } } } while (0)
; #define SG_PV() do { if (SGP) { __builtin_amdgcn_sched_group_barrier(0x100, SGP_PRE, 0); if constexpr (MODE == 0) { _Pragma("unroll") for (int _g = 0; _g < 4; ++_g) SG_ONE(2, 24, 4); } else { _Pragma("unroll") for (int _g = 0; _g < 16; ++_g) SG_ONE(2, 6, 1); } } } while (0)
; #define RESC(a) do { if (__any((a) < 1.f)) { if (hi == 0) al_l[r32] = (a); asm volatile("s_waitcnt lgkmcnt(0)" ::: "memory"); \
;     _Pragma("unroll") for (int d = 0; d < 4; ++d) _Pragma("unroll") for (int r = 0; r < 16; ++r) o[d][r] *= al_l[crow(r, hi)]; } } while (0)
; template <int MODE, int SD> ...
;     ...
;   for (int j = 1; j + 1 < NT; j += 2) {
;     SBAR(); qkt<MODE>(pB0, pB1, K_lds + SHM_K, Kr_lds + SHM_KR, Qr_l, qr, q8, r32, hi);
;     FSM(pA0, pA1, alA); SG_QKT(); SBAR();
;     SLOAD(SO, (j + SD) * KVBLK); SBAR();
;     PVC(0); partialSM<MODE>(pB0, pB1, m_reg, mnB, alB, C, kbl + j * KVBLK, btab, nomask); asm volatile("" : "+v"(pB0), "+v"(pB1), "+v"(alB)); SG_PV(); SBAR();
;     __syncthreads(); SWAIT(); SWRITE(0, SE);
;     RESC(alB); __syncthreads();
;     SBAR(); qkt<MODE>(pA0, pA1, K_lds, Kr_lds, Qr_l, qr, q8, r32, hi);
;     FSM(pB0, pB1, alB); SG_QKT(); SBAR();
;     if (SD == 1 || j + 3 < NT) SLOAD(SE, (j + 1 + SD) * KVBLK); SBAR();
;     PVC(SHM_V); partialSM<MODE>(pA0, pA1, m_reg, mnA, alA, C, kbl + (j + 1) * KVBLK, btab, nomask); asm volatile("" : "+v"(pA0), "+v"(pA1), "+v"(alA)); SG_PV(); SBAR();
;     __syncthreads(); SWAIT(); SWRITE(1, SO);
;     RESC(alA); __syncthreads();
	v_mul_f32_e32 v66, 0xbdd53b94, v238
	v_cmp_gt_f32_e32 vcc, 1.0, v0
	s_nop 0
	v_mfma_scale_f32_32x32x64_f8f6f4 v[50:65], v[170:177], v[154:161], v[50:65], v216, v216 op_sel_hi:[0,0,0]
	v_fmamk_f32 v82, v82, 0x3dd53b94, v66
	v_fmamk_f32 v83, v83, 0x3dd53b94, v66
	v_fmamk_f32 v84, v84, 0x3dd53b94, v66
	v_fmamk_f32 v85, v85, 0x3dd53b94, v66
	v_exp_f32_e32 v82, v82
	v_exp_f32_e32 v83, v83
	v_exp_f32_e32 v84, v84
	v_exp_f32_e32 v85, v85
	v_mfma_scale_f32_32x32x64_f8f6f4 v[34:49], v[170:177], v[146:153], v[34:49], v216, v216 op_sel_hi:[0,0,0]
	v_fmamk_f32 v86, v86, 0x3dd53b94, v66
	v_fmamk_f32 v87, v87, 0x3dd53b94, v66
	v_fmamk_f32 v88, v88, 0x3dd53b94, v66
	v_fmamk_f32 v89, v89, 0x3dd53b94, v66
	v_exp_f32_e32 v86, v86
	v_exp_f32_e32 v87, v87
	v_exp_f32_e32 v88, v88
	v_exp_f32_e32 v89, v89
	v_mfma_scale_f32_32x32x64_f8f6f4 v[18:33], v[170:177], v[122:129], v[18:33], v216, v216 op_sel_hi:[0,0,0]
	v_fmamk_f32 v90, v90, 0x3dd53b94, v66
	v_fmamk_f32 v91, v91, 0x3dd53b94, v66
	v_fmamk_f32 v92, v92, 0x3dd53b94, v66
	v_fmamk_f32 v93, v93, 0x3dd53b94, v66
	v_exp_f32_e32 v90, v90
	v_exp_f32_e32 v91, v91
	v_exp_f32_e32 v92, v92
	v_exp_f32_e32 v93, v93
	v_mfma_scale_f32_32x32x64_f8f6f4 v[2:17], v[170:177], v[162:169], v[2:17], v216, v216 op_sel_hi:[0,0,0]
	v_fmamk_f32 v94, v94, 0x3dd53b94, v66
	v_fmamk_f32 v95, v95, 0x3dd53b94, v66
	v_fmamk_f32 v96, v96, 0x3dd53b94, v66
	v_fmamk_f32 v97, v97, 0x3dd53b94, v66
	v_exp_f32_e32 v94, v94
	v_exp_f32_e32 v95, v95
	v_exp_f32_e32 v96, v96
	v_exp_f32_e32 v97, v97
	v_pk_fma_f32 v[98:99], v[98:99], s[78:79], v[66:67] op_sel_hi:[1,0,0]
	v_pk_fma_f32 v[100:101], v[100:101], s[78:79], v[66:67] op_sel_hi:[1,0,0]
	v_pk_fma_f32 v[102:103], v[102:103], s[78:79], v[66:67] op_sel_hi:[1,0,0]
	v_pk_fma_f32 v[104:105], v[104:105], s[78:79], v[66:67] op_sel_hi:[1,0,0]
	v_pk_fma_f32 v[106:107], v[106:107], s[78:79], v[66:67] op_sel_hi:[1,0,0]
	v_pk_fma_f32 v[108:109], v[108:109], s[78:79], v[66:67] op_sel_hi:[1,0,0]
	v_pk_fma_f32 v[110:111], v[110:111], s[78:79], v[66:67] op_sel_hi:[1,0,0]
	v_pk_fma_f32 v[112:113], v[112:113], s[78:79], v[66:67] op_sel_hi:[1,0,0]
	s_cbranch_vccz .LBB0_671
	s_and_saveexec_b64 s[20:21], s[8:9]
	ds_write_b32 v229, v0 offset:128
	s_or_b64 exec, exec, s[20:21]
	s_waitcnt lgkmcnt(0)
	ds_read_b128 v[66:69], v228 offset:224
	ds_read_b128 v[70:73], v228 offset:192
	ds_read_b128 v[74:77], v228 offset:160
	ds_read_b128 v[78:81], v228 offset:128
	s_waitcnt lgkmcnt(3)
	s_nop 7
	v_pk_mul_f32 v[64:65], v[64:65], v[68:69]
	s_waitcnt lgkmcnt(2)
	v_pk_mul_f32 v[60:61], v[60:61], v[72:73]
	s_waitcnt lgkmcnt(1)
	v_pk_mul_f32 v[56:57], v[56:57], v[76:77]
	s_waitcnt lgkmcnt(0)
	v_pk_mul_f32 v[52:53], v[52:53], v[80:81]
	v_pk_mul_f32 v[62:63], v[62:63], v[66:67]
	v_pk_mul_f32 v[58:59], v[58:59], v[70:71]
	v_pk_mul_f32 v[54:55], v[54:55], v[74:75]
	v_pk_mul_f32 v[50:51], v[50:51], v[78:79]
	v_pk_mul_f32 v[48:49], v[48:49], v[68:69]
	v_pk_mul_f32 v[44:45], v[44:45], v[72:73]
	v_pk_mul_f32 v[40:41], v[40:41], v[76:77]
	v_pk_mul_f32 v[36:37], v[36:37], v[80:81]
	v_pk_mul_f32 v[46:47], v[46:47], v[66:67]
	v_pk_mul_f32 v[42:43], v[42:43], v[70:71]
	v_pk_mul_f32 v[38:39], v[38:39], v[74:75]
	v_pk_mul_f32 v[34:35], v[34:35], v[78:79]
	v_pk_mul_f32 v[32:33], v[32:33], v[68:69]
	v_pk_mul_f32 v[28:29], v[28:29], v[72:73]
	v_pk_mul_f32 v[24:25], v[24:25], v[76:77]
	v_pk_mul_f32 v[20:21], v[20:21], v[80:81]
	v_pk_mul_f32 v[30:31], v[30:31], v[66:67]
	v_pk_mul_f32 v[26:27], v[26:27], v[70:71]
	v_pk_mul_f32 v[22:23], v[22:23], v[74:75]
	v_pk_mul_f32 v[18:19], v[18:19], v[78:79]
	v_pk_mul_f32 v[16:17], v[16:17], v[68:69]
	v_pk_mul_f32 v[12:13], v[12:13], v[72:73]
	v_pk_mul_f32 v[8:9], v[8:9], v[76:77]
	v_pk_mul_f32 v[4:5], v[4:5], v[80:81]
	v_pk_mul_f32 v[14:15], v[14:15], v[66:67]
	v_pk_mul_f32 v[10:11], v[10:11], v[70:71]
	v_pk_mul_f32 v[6:7], v[6:7], v[74:75]
	v_pk_mul_f32 v[2:3], v[2:3], v[78:79]
.LBB0_671:
	s_waitcnt vmcnt(0)
	s_waitcnt vmcnt(1)
	ds_write_b128 v225, v[182:185]
	s_waitcnt vmcnt(0)
	ds_write_b128 v226, v[186:189] offset:32768
	s_and_saveexec_b64 s[20:21], s[12:13]
	ds_write_b128 v234, v[178:181] offset:32768
	s_or_b64 exec, exec, s[20:21]
	s_lshl_b32 s26, s25, 6
	s_waitcnt lgkmcnt(0)
	s_barrier
	ds_read_b128 v[66:69], v231 offset:32768
	ds_read_b128 v[70:73], v231 offset:32784
	global_load_dwordx4 v[182:185], v[208:209], off offset:64
	global_load_dwordx4 v[186:189], v[206:207], off
	s_and_saveexec_b64 s[20:21], s[12:13]
	global_load_dwordx4 v[178:181], v[204:205], off
	s_or_b64 exec, exec, s[20:21]
	v_lshl_add_u64 v[206:207], v[206:207], 0, v[212:213]
	v_lshl_add_u64 v[204:205], v[204:205], 0, v[210:211]
	ds_read_b128 v[122:125], v231 offset:32832
	ds_read_b128 v[126:129], v231 offset:32848
	ds_read_b128 v[162:165], v231 offset:32896
	ds_read_b128 v[166:169], v231 offset:32912
	ds_read_b128 v[146:149], v231 offset:39424
	ds_read_b128 v[150:153], v231 offset:39440
	ds_read_b128 v[154:157], v231 offset:39488
	ds_read_b128 v[158:161], v231 offset:39504
	ds_read_b128 v[170:173], v231 offset:39552
	ds_read_b128 v[174:177], v231 offset:39568
	s_waitcnt lgkmcnt(10)
	v_mfma_scale_f32_32x32x64_f8f6f4 v[66:81], v[66:73], v[114:121], 0, v216, v216 op_sel_hi:[0,0,0]
	v_exp_f32_e32 v243, v98
	v_exp_f32_e32 v244, v99
	v_exp_f32_e32 v241, v100
	v_exp_f32_e32 v242, v101
	v_exp_f32_e32 v247, v102
	v_exp_f32_e32 v248, v103
	v_add_f32_e32 v239, 0, v82
	v_add_f32_e32 v239, v83, v239
	s_waitcnt lgkmcnt(8)
	v_mfma_scale_f32_32x32x64_f8f6f4 v[66:81], v[122:129], v[130:137], v[66:81], v216, v216 op_sel_hi:[0,0,0]
	v_exp_f32_e32 v245, v104
	v_exp_f32_e32 v246, v105
	v_exp_f32_e32 v249, v106
	v_exp_f32_e32 v252, v107
	v_exp_f32_e32 v250, v108
	v_exp_f32_e32 v251, v109
	v_add_f32_e32 v239, v84, v239
	v_add_f32_e32 v240, v244, v243
	v_add_f32_e32 v239, v85, v239
	v_add_f32_e32 v240, v241, v240
	v_add_f32_e32 v240, v242, v240
	s_waitcnt lgkmcnt(6)
; __device__ __forceinline__ unsigned pk4_fp8(float a, float b, float c, float d) { int p = __builtin_amdgcn_cvt_pk_fp8_f32(a, b, 0, false); p = __builtin_amdgcn_cvt_pk_fp8_f32(c, d, p, true); return (unsigned)p; }
; template <int MODE>
; __device__ __forceinline__ void partialSM(f32x16& p0, f32x16& p1, float& m_reg, float& mn, float& alpha, const float C, int kb, const float* btab, const bool nomask) {
;     ...
;     float pmax = p0[0];
; #pragma unroll
;     for (int r = 1; r < 16; ++r) pmax = fmaxf(pmax, p0[r]);
; #pragma unroll
;     for (int r = 0; r < 16; ++r) pmax = fmaxf(pmax, p1[r]);
;     { auto rr = __builtin_amdgcn_permlane32_swap(__float_as_uint(pmax), __float_as_uint(pmax), false, false); pmax = fmaxf(__uint_as_float(rr[0]), __uint_as_float(rr[1])); }
;     { const bool keep = __all((pmax - m_reg) * C <= (MODE == 0 ? 7.5f : 11.5f)); mn = keep ? m_reg : fmaxf(m_reg, pmax);   alpha = __builtin_amdgcn_exp2f((m_reg - mn) * C); m_reg = mn; }
;     const float mnC = -mn * C;
; #pragma unroll
;     for (int r = 0; r < 16; ++r) p0[r] = fmaf(p0[r], C, mnC);
; #pragma unroll
;     for (int r = 0; r < 16; ++r) p1[r] = fmaf(p1[r], C, mnC);
; #pragma unroll
;     for (int r = 0; r < 16; ++r) p0[r] = __builtin_amdgcn_exp2f(p0[r]);
; __device__ __forceinline__ void finishSM8(f32x16& p0, f32x16& p1, float alpha, float& l_reg, bf16x8& pa0, bf16x8& pa1) {
; #pragma unroll
;   for (int r = 0; r < 16; ++r) p1[r] = __builtin_amdgcn_exp2f(p1[r]);
;   float ps = 0;
; #pragma unroll
;   for (int r = 0; r < 16; ++r) ps += p0[r];
; #pragma unroll
;   for (int r = 0; r < 16; ++r) ps += p1[r];
;   { auto rr = __builtin_amdgcn_permlane32_swap(__float_as_uint(ps), __float_as_uint(ps), false, false); ps = __uint_as_float(rr[0]) + __uint_as_float(rr[1]); }
;   l_reg = l_reg * alpha + ps;
;   const u32x4 w0 = {pk4_fp8(p0[0], p0[1], p0[2], p0[3]), pk4_fp8(p0[4], p0[5], p0[6], p0[7]), pk4_fp8(p0[8], p0[9], p0[10], p0[11]), pk4_fp8(p0[12], p0[13], p0[14], p0[15])};
;   const u32x4 w1 = {pk4_fp8(p1[0], p1[1], p1[2], p1[3]), pk4_fp8(p1[4], p1[5], p1[6], p1[7]), pk4_fp8(p1[8], p1[9], p1[10], p1[11]), pk4_fp8(p1[12], p1[13], p1[14], p1[15])};
;   pa0 = __builtin_bit_cast(bf16x8, w0); pa1 = __builtin_bit_cast(bf16x8, w1);
	v_mfma_scale_f32_32x32x64_f8f6f4 v[66:81], v[162:169], v[138:145], v[66:81], v216, v216 op_sel_hi:[0,0,0]
	v_exp_f32_e32 v254, v110
	v_exp_f32_e32 v191, v111
	v_exp_f32_e32 v253, v112
	v_exp_f32_e32 v217, v113
	v_add_f32_e32 v239, v86, v239
	v_add_f32_e32 v240, v247, v240
	v_add_f32_e32 v239, v87, v239
	v_add_f32_e32 v240, v248, v240
	v_add_f32_e32 v239, v88, v239
	v_add_f32_e32 v240, v245, v240
	v_add_f32_e32 v239, v89, v239
	v_add_f32_e32 v240, v246, v240
	s_waitcnt lgkmcnt(4)
	v_mfma_scale_f32_32x32x64_f8f6f4 v[98:113], v[146:153], v[114:121], 0, v216, v216 op_sel_hi:[0,0,0]
	v_add_f32_e32 v239, v90, v239
	v_add_f32_e32 v240, v249, v240
	v_add_f32_e32 v239, v91, v239
	v_add_f32_e32 v240, v252, v240
	v_add_f32_e32 v239, v92, v239
	v_add_f32_e32 v240, v250, v240
	v_add_f32_e32 v239, v93, v239
	v_add_f32_e32 v240, v251, v240
	v_add_f32_e32 v239, v94, v239
	v_add_f32_e32 v240, v254, v240
	s_waitcnt lgkmcnt(2)
	v_mfma_scale_f32_32x32x64_f8f6f4 v[98:113], v[154:161], v[130:137], v[98:113], v216, v216 op_sel_hi:[0,0,0]
	v_add_f32_e32 v239, v95, v239
	v_add_f32_e32 v240, v191, v240
	v_add_f32_e32 v239, v96, v239
	v_add_f32_e32 v240, v253, v240
	v_add_f32_e32 v239, v97, v239
	v_add_f32_e32 v240, v217, v240
	v_add_f32_e32 v239, v240, v239
	v_mov_b32_e32 v240, v239
	s_waitcnt lgkmcnt(0)
	v_mfma_scale_f32_32x32x64_f8f6f4 v[98:113], v[170:177], v[138:145], v[98:113], v216, v216 op_sel_hi:[0,0,0]
	s_nop 0
	v_permlane32_swap_b32_e32 v239, v240
	ds_read_b128 v[154:157], v230 offset:18432
	ds_read_b128 v[158:161], v230 offset:18448
	ds_read_b128 v[146:149], v230 offset:20992
	ds_read_b128 v[150:153], v230 offset:21008
	ds_read_b128 v[122:125], v230 offset:23552
	ds_read_b128 v[126:129], v230 offset:23568
	ds_read_b128 v[166:169], v230 offset:26128
	v_cvt_pk_fp8_f32 v82, v82, v83
	v_cvt_pk_fp8_f32 v83, v86, v87
	v_cvt_pk_fp8_f32 v82, v84, v85 op_sel:[0,0,1]
	v_cvt_pk_fp8_f32 v83, v88, v89 op_sel:[0,0,1]
	v_cvt_pk_fp8_f32 v84, v90, v91
	v_cvt_pk_fp8_f32 v85, v94, v95
	v_cvt_pk_fp8_f32 v84, v92, v93 op_sel:[0,0,1]
	v_cvt_pk_fp8_f32 v85, v96, v97 op_sel:[0,0,1]
	v_cvt_pk_fp8_f32 v86, v243, v244
	v_cvt_pk_fp8_f32 v87, v247, v248
	v_cvt_pk_fp8_f32 v86, v241, v242 op_sel:[0,0,1]
	v_cvt_pk_fp8_f32 v87, v245, v246 op_sel:[0,0,1]
	v_cvt_pk_fp8_f32 v88, v249, v252
	v_cvt_pk_fp8_f32 v89, v254, v191
	v_cvt_pk_fp8_f32 v88, v250, v251 op_sel:[0,0,1]
	v_cvt_pk_fp8_f32 v89, v253, v217 op_sel:[0,0,1]
	v_max_f32_e32 v162, v67, v67
	v_max_f32_e32 v164, v98, v98
	v_max_f32_e32 v163, v66, v66
	v_max3_f32 v164, v164, v99, v100
	v_max_f32_e32 v162, v163, v162
	v_max3_f32 v164, v164, v101, v102
	v_max3_f32 v162, v162, v68, v69
	v_max3_f32 v164, v164, v103, v104
	v_max3_f32 v162, v162, v70, v71
	v_max3_f32 v164, v164, v105, v106
	v_max3_f32 v162, v162, v72, v73
	v_max3_f32 v164, v164, v107, v108
	v_max3_f32 v162, v162, v74, v75
	v_max3_f32 v164, v164, v109, v110
	v_max3_f32 v162, v162, v76, v77
	v_max3_f32 v164, v164, v111, v112
	v_max3_f32 v162, v162, v78, v79
	v_max_f32_e32 v164, v164, v113
	v_max3_f32 v162, v162, v80, v81
	v_max_f32_e32 v162, v162, v164
	v_mov_b32_e32 v163, v162
	s_nop 1
	v_permlane32_swap_b32_e32 v162, v163
	v_max_f32_e32 v163, v163, v163
	v_max_f32_e32 v162, v162, v162
	v_max_f32_e32 v162, v162, v163
	v_sub_f32_e32 v163, v162, v238
	v_mul_f32_e32 v163, 0x3dd53b94, v163
	v_cmp_ge_f32_e32 vcc, s57, v163
	s_cmp_eq_u64 vcc, exec
	v_max_f32_e32 v163, v238, v238
	s_cselect_b64 vcc, -1, 0
	v_max_f32_e32 v162, v163, v162
	v_cndmask_b32_e32 v237, v162, v238, vcc
	v_sub_f32_e32 v170, v238, v237
	v_mul_f32_e32 v170, 0x3dd53b94, v170
	v_exp_f32_e32 v170, v170
	ds_read_b128 v[162:165], v230 offset:26112
	s_waitcnt lgkmcnt(0)
	v_mul_f32_e32 v172, 0xbdd53b94, v237
	v_cmp_gt_f32_e32 vcc, 1.0, v170
	s_nop 0
	v_mfma_scale_f32_32x32x64_f8f6f4 v[50:65], v[82:89], v[154:161], v[50:65], v216, v216 op_sel_hi:[0,0,0]
	v_fmamk_f32 v66, v66, 0x3dd53b94, v172
	v_fmamk_f32 v67, v67, 0x3dd53b94, v172
	v_fmamk_f32 v68, v68, 0x3dd53b94, v172
	v_fmamk_f32 v69, v69, 0x3dd53b94, v172
	v_exp_f32_e32 v66, v66
	v_exp_f32_e32 v67, v67
	v_exp_f32_e32 v68, v68
	v_exp_f32_e32 v69, v69
	v_mfma_scale_f32_32x32x64_f8f6f4 v[34:49], v[82:89], v[146:153], v[34:49], v216, v216 op_sel_hi:[0,0,0]
	v_fmamk_f32 v70, v70, 0x3dd53b94, v172
	v_fmamk_f32 v71, v71, 0x3dd53b94, v172
	v_fmamk_f32 v72, v72, 0x3dd53b94, v172
	v_fmamk_f32 v73, v73, 0x3dd53b94, v172
	v_exp_f32_e32 v70, v70
	v_exp_f32_e32 v71, v71
	v_exp_f32_e32 v72, v72
	v_exp_f32_e32 v73, v73
	v_mfma_scale_f32_32x32x64_f8f6f4 v[18:33], v[82:89], v[122:129], v[18:33], v216, v216 op_sel_hi:[0,0,0]
	v_fmamk_f32 v74, v74, 0x3dd53b94, v172
	v_fmamk_f32 v75, v75, 0x3dd53b94, v172
	v_fmamk_f32 v76, v76, 0x3dd53b94, v172
	v_fmamk_f32 v77, v77, 0x3dd53b94, v172
	v_exp_f32_e32 v74, v74
	v_exp_f32_e32 v75, v75
	v_exp_f32_e32 v76, v76
	v_exp_f32_e32 v77, v77
	v_mfma_scale_f32_32x32x64_f8f6f4 v[2:17], v[82:89], v[162:169], v[2:17], v216, v216 op_sel_hi:[0,0,0]
	v_fmamk_f32 v78, v78, 0x3dd53b94, v172
	v_fmamk_f32 v79, v79, 0x3dd53b94, v172
	v_fmamk_f32 v80, v80, 0x3dd53b94, v172
	v_fmamk_f32 v81, v81, 0x3dd53b94, v172
	v_exp_f32_e32 v78, v78
	v_exp_f32_e32 v79, v79
	v_exp_f32_e32 v80, v80
	v_exp_f32_e32 v81, v81
	v_pk_fma_f32 v[98:99], v[98:99], s[78:79], v[172:173] op_sel_hi:[1,0,0]
	v_pk_fma_f32 v[100:101], v[100:101], s[78:79], v[172:173] op_sel_hi:[1,0,0]
	v_pk_fma_f32 v[102:103], v[102:103], s[78:79], v[172:173] op_sel_hi:[1,0,0]
	v_pk_fma_f32 v[104:105], v[104:105], s[78:79], v[172:173] op_sel_hi:[1,0,0]
	v_pk_fma_f32 v[106:107], v[106:107], s[78:79], v[172:173] op_sel_hi:[1,0,0]
	v_pk_fma_f32 v[108:109], v[108:109], s[78:79], v[172:173] op_sel_hi:[1,0,0]
	v_pk_fma_f32 v[110:111], v[110:111], s[78:79], v[172:173] op_sel_hi:[1,0,0]
	v_pk_fma_f32 v[112:113], v[112:113], s[78:79], v[172:173] op_sel_hi:[1,0,0]
	s_cbranch_vccz .LBB0_654
	s_and_saveexec_b64 s[20:21], s[8:9]
	s_cbranch_execz .LBB0_653
	ds_write_b32 v229, v170 offset:128
	s_branch .LBB0_653
